# mid-in-proj and compress-done arrivals are fire-and-forget atomics; only the workgroups that consume wait
# speedup vs baseline: 1.0142x; 1.0024x over previous
; __device__ void phase_x(const Params& p, int layer, unsigned char* smem) {
;     ...
;   for (int i = blockIdx.x; i < NC; i += G) {
;     int t = i; int ct = t & 7; t >>= 3; int g = t & 1; t >>= 1; int b = t & 7; int kv = t >> 3;
;     item_compress(p, layer, kv, b, g, ct, smem);
;   }
.LBB0_238:
	s_waitcnt lgkmcnt(0)
	v_readlane_b32 s18, v255, 60
	s_cmp_lg_u32 s18, 1
	s_cbranch_scc1 .Lxh2_done
	v_readlane_b32 s18, v255, 63
	s_cmp_lg_u32 s18, 0
	s_cbranch_scc1 .Lxh2_p1
	s_mov_b32 s18, 1
	v_writelane_b32 v255, s18, 63
	v_readlane_b32 s18, v253, 0
	s_cmpk_ge_u32 s18, 0x100
	s_cbranch_scc1 .Lxh2_go
	s_waitcnt vmcnt(0) lgkmcnt(0)
	s_barrier
	v_cmp_eq_u32_e32 vcc, 0, v210
	s_and_saveexec_b64 s[0:1], vcc
	s_cbranch_execz .Lxh2_e
	v_readlane_b32 s6, v255, 58
	v_readlane_b32 s7, v255, 59
	v_mov_b32_e32 v0, 1
	s_nop 3
	global_atomic_add v1, v0, s[6:7] offset:64

; __device__ void phase_inproj(const Params& p, int layer, unsigned char* smem) {
;     ...
;   for (int idx = loc; idx < 8 * NT_IN; idx += nloc) {
;     int grp = idx / (2 * NT_IN), within = idx % (2 * NT_IN);
;     int nt = within >> 1, mt = xcd * 8 + grp * 2 + (within & 1);
;     int vbase = -1;
;     if (nt == 4) vbase = 0; else if (nt == 5) vbase = 128; else if (nt == 11) vbase = 256;
;     else if (nt == 21) vbase = 384; else if (nt == 23) vbase = 512;
;     if (vbase >= 0) gemm_tile2<1>(P_XN, DM, W, DM, DM, mt * 256, nt * 128, P_VT, vbase, nullptr, nullptr, smem);
;     else gemm_tile2<0>(P_XN, DM, W, DM, DM, mt * 256, nt * 128, P_H, 0, nullptr, nullptr, smem);
;   }
.LBB0_286:
	s_add_i32 s29, s29, s12
	v_readlane_b32 s0, v255, 60
	s_cmp_lg_u32 s0, 1
	s_cbranch_scc1 .Limid_done
	s_cmpk_lt_u32 s29, 0xc0
	s_cbranch_scc1 .Limid_done
	s_cmpk_gt_u32 s29, 0xff
	s_cbranch_scc1 .Limid_done
	s_waitcnt vmcnt(0) lgkmcnt(0)
	s_barrier
	v_cmp_eq_u32_e32 vcc, 0, v210
	s_and_saveexec_b64 s[0:1], vcc
	s_cbranch_execz .Limid_x
	v_readlane_b32 s6, v255, 58
	v_readlane_b32 s7, v255, 59
	v_mov_b32_e32 v0, 1
	s_nop 3
	global_atomic_add v1, v0, s[6:7] offset:32
	s_cmpk_lt_u32 s29, 0xe8
	s_cbranch_scc1 .Limid_x
	v_readlane_b32 s25, v255, 21
	s_add_i32 s25, s25, 1
	s_lshl_b32 s25, s25, 6
	s_mov_b32 s24, 0
.Limid_p:
	global_load_dword v0, v1, s[6:7] offset:32 sc1
	s_waitcnt vmcnt(0)
	v_readfirstlane_b32 s18, v0
	s_cmp_ge_u32 s18, s25
	s_cbranch_scc1 .Limid_acq
	s_sleep 2
	s_add_i32 s24, s24, 1
	s_cmp_lt_u32 s24, 0x100000
	s_cbranch_scc1 .Limid_p

; __device__ void phase_inproj(const Params& p, int layer, unsigned char* smem) {
;     ...
;   for (int idx = loc; idx < 8 * NT_IN; idx += nloc) {
;     int grp = idx / (2 * NT_IN), within = idx % (2 * NT_IN);
;     int nt = within >> 1, mt = xcd * 8 + grp * 2 + (within & 1);
;     int vbase = -1;
;     if (nt == 4) vbase = 0; else if (nt == 5) vbase = 128; else if (nt == 11) vbase = 256;
;     else if (nt == 21) vbase = 384; else if (nt == 23) vbase = 512;
;     if (vbase >= 0) gemm_tile2<1>(P_XN, DM, W, DM, DM, mt * 256, nt * 128, P_VT, vbase, nullptr, nullptr, smem);
;     else gemm_tile2<0>(P_XN, DM, W, DM, DM, mt * 256, nt * 128, P_H, 0, nullptr, nullptr, smem);
;   }
.Limid_x:
	s_or_b64 exec, exec, s[0:1]
	s_cmpk_lt_u32 s29, 0xe8
	s_cbranch_scc1 .Limid_done
	s_barrier

; __device__ __forceinline__ unsigned xb_ld(unsigned* p)              { return __hip_atomic_load(p, __ATOMIC_RELAXED, __HIP_MEMORY_SCOPE_AGENT); }
; #define XB_SPIN(cond, bar) do { unsigned _sp = 0; while (cond) { __builtin_amdgcn_s_sleep(1); \
;     if ((++_sp & 255u) == 0u) { if (xb_ld(&(bar)[XB_TMO])) break; if (_sp > XB_SPIN_CAP) { atomicAdd(&(bar)[XB_TMO], 1u); break; } } } } while (0)
; __device__ __forceinline__ void xcd_barrier(const XcdBarrier& b) {
;     ...
;         } else {
;             XB_SPIN(xb_ld(&bar[XB_XGEN(b.x)]) == gen, bar);
;             __builtin_amdgcn_fence(__ATOMIC_ACQUIRE, "agent");
;             asm volatile("s_waitcnt vmcnt(0)" ::: "memory");
.Lxbar:
	s_waitcnt vmcnt(0) lgkmcnt(0)
	s_barrier
	v_cmp_eq_u32_e32 vcc, 0, v210
	s_and_saveexec_b64 s[0:1], vcc
	s_cbranch_execz .Llbar_x
	v_readlane_b32 s6, v255, 58
	v_readlane_b32 s7, v255, 59
	s_add_i32 s9, s52, 2
	s_mul_i32 s9, s9, 0x3334
	s_lshr_b32 s9, s9, 16
	s_lshl_b32 s9, s9, 5

; __device__ __forceinline__ unsigned xb_ld(unsigned* p)              { return __hip_atomic_load(p, __ATOMIC_RELAXED, __HIP_MEMORY_SCOPE_AGENT); }
; #define XB_SPIN(cond, bar) do { unsigned _sp = 0; while (cond) { __builtin_amdgcn_s_sleep(1); \
;     if ((++_sp & 255u) == 0u) { if (xb_ld(&(bar)[XB_TMO])) break; if (_sp > XB_SPIN_CAP) { atomicAdd(&(bar)[XB_TMO], 1u); break; } } } } while (0)
; __device__ __forceinline__ void xcd_barrier(const XcdBarrier& b) {
;     ...
;         } else {
;             XB_SPIN(xb_ld(&bar[XB_XGEN(b.x)]) == gen, bar);
;             __builtin_amdgcn_fence(__ATOMIC_ACQUIRE, "agent");
;             asm volatile("s_waitcnt vmcnt(0)" ::: "memory");
.Lxbar_p:
	s_sleep 1
	global_load_dword v0, v1, s[6:7] offset:64 sc1
	s_waitcnt vmcnt(0)
	v_readfirstlane_b32 s18, v0
	s_cmp_ge_u32 s18, s9
	s_cbranch_scc1 .Llbar_acq
	s_add_i32 s8, s8, 1
	s_cmp_lt_u32 s8, 0x100000
	s_cbranch_scc1 .Lxbar_p
	s_branch .Llbar_acq
